# grid barriers: waiting workgroups issue the acquire L1 invalidate with their first poll instead of after the release (v29 + earlyinv)
# speedup vs baseline: 1.0079x; 1.0079x over previous
.LBB0_182:
	s_or_b64 exec, exec, s[12:13]
	v_cvt_f32_u32_e32 v4, v2
	s_waitcnt vmcnt(0)
	v_readfirstlane_b32 s10, v3
	v_sub_u32_e32 v3, 0, v2
	v_rcp_iflag_f32_e32 v4, v4
	v_add_u32_e32 v5, s10, v1
	v_mul_f32_e32 v4, 0x4f7ffffe, v4
	v_cvt_u32_f32_e32 v4, v4
	v_mul_lo_u32 v1, v3, v4
	v_mul_hi_u32 v1, v4, v1
	v_add_u32_e32 v1, v4, v1
	v_mul_hi_u32 v1, v5, v1
	v_mul_lo_u32 v3, v1, v2
	v_sub_u32_e32 v3, v5, v3
	v_add_u32_e32 v4, 1, v1
	v_cmp_ge_u32_e32 vcc, v3, v2
	s_nop 1
	v_cndmask_b32_e32 v1, v1, v4, vcc
	v_sub_u32_e32 v4, v3, v2
	v_cndmask_b32_e32 v3, v3, v4, vcc
	v_add_u32_e32 v4, 1, v1
	v_cmp_ge_u32_e32 vcc, v3, v2
	v_add_u32_e32 v3, 1, v5
	s_nop 0
	v_cndmask_b32_e32 v1, v1, v4, vcc
	v_mul_lo_u32 v4, v2, v1
	v_add_u32_e32 v2, v4, v2
	v_cmp_ne_u32_e32 vcc, v3, v2
	s_and_saveexec_b64 s[10:11], vcc
	s_xor_b64 s[10:11], exec, s[10:11]
	s_cbranch_execz .LBB0_196
	s_waitcnt lgkmcnt(0)
	v_mov_b32_e32 v0, 0x2000
	global_load_dword v0, v0, s[8:9] offset:1024 sc1
	buffer_inv sc1
	s_add_u32 s16, s8, 0x2400
	s_addc_u32 s17, s9, 0
	s_waitcnt vmcnt(0)
	v_cmp_eq_u32_e32 vcc, v0, v1
	s_and_saveexec_b64 s[12:13], vcc
	s_cbranch_execz .LBB0_195
	s_add_u32 s14, s6, 0x4200
	s_addc_u32 s15, s7, 0
	s_mov_b32 s28, 1
	s_mov_b64 s[18:19], 0
	v_mov_b32_e32 v0, 0
	s_branch .LBB0_186

.LBB0_195:
	s_or_b64 exec, exec, s[12:13]
	s_waitcnt vmcnt(0)
	s_waitcnt vmcnt(0)

.LBB0_481:
	s_or_b64 exec, exec, s[12:13]
	v_cvt_f32_u32_e32 v4, v2
	s_waitcnt vmcnt(0)
	v_readfirstlane_b32 s10, v3
	v_sub_u32_e32 v3, 0, v2
	v_rcp_iflag_f32_e32 v4, v4
	v_add_u32_e32 v5, s10, v1
	v_mul_f32_e32 v4, 0x4f7ffffe, v4
	v_cvt_u32_f32_e32 v4, v4
	v_mul_lo_u32 v1, v3, v4
	v_mul_hi_u32 v1, v4, v1
	v_add_u32_e32 v1, v4, v1
	v_mul_hi_u32 v1, v5, v1
	v_mul_lo_u32 v3, v1, v2
	v_sub_u32_e32 v3, v5, v3
	v_add_u32_e32 v4, 1, v1
	v_cmp_ge_u32_e32 vcc, v3, v2
	s_nop 1
	v_cndmask_b32_e32 v1, v1, v4, vcc
	v_sub_u32_e32 v4, v3, v2
	v_cndmask_b32_e32 v3, v3, v4, vcc
	v_add_u32_e32 v4, 1, v1
	v_cmp_ge_u32_e32 vcc, v3, v2
	v_add_u32_e32 v3, 1, v5
	s_nop 0
	v_cndmask_b32_e32 v1, v1, v4, vcc
	v_mul_lo_u32 v4, v2, v1
	v_add_u32_e32 v2, v4, v2
	v_cmp_ne_u32_e32 vcc, v3, v2
	s_and_saveexec_b64 s[10:11], vcc
	s_xor_b64 s[10:11], exec, s[10:11]
	s_cbranch_execz .LBB0_495
	s_waitcnt lgkmcnt(0)
	v_mov_b32_e32 v0, 0x2000
	global_load_dword v0, v0, s[8:9] offset:1024 sc1
	buffer_inv sc1
	s_add_u32 s18, s8, 0x2400
	s_addc_u32 s19, s9, 0
	s_waitcnt vmcnt(0)
	v_cmp_eq_u32_e32 vcc, v0, v1
	s_and_saveexec_b64 s[12:13], vcc
	s_cbranch_execz .LBB0_494
	s_add_u32 s16, s6, 0x4200
	s_addc_u32 s17, s7, 0
	s_mov_b32 s30, 1
	s_mov_b64 s[20:21], 0
	v_mov_b32_e32 v0, 0
	s_branch .LBB0_485

.LBB0_630:
	s_or_b64 exec, exec, s[14:15]
	v_cvt_f32_u32_e32 v4, v2
	s_waitcnt vmcnt(0)
	v_readfirstlane_b32 s12, v3
	v_sub_u32_e32 v3, 0, v2
	v_rcp_iflag_f32_e32 v4, v4
	v_add_u32_e32 v5, s12, v1
	v_mul_f32_e32 v4, 0x4f7ffffe, v4
	v_cvt_u32_f32_e32 v4, v4
	v_mul_lo_u32 v1, v3, v4
	v_mul_hi_u32 v1, v4, v1
	v_add_u32_e32 v1, v4, v1
	v_mul_hi_u32 v1, v5, v1
	v_mul_lo_u32 v3, v1, v2
	v_sub_u32_e32 v3, v5, v3
	v_add_u32_e32 v4, 1, v1
	v_cmp_ge_u32_e32 vcc, v3, v2
	s_nop 1
	v_cndmask_b32_e32 v1, v1, v4, vcc
	v_sub_u32_e32 v4, v3, v2
	v_cndmask_b32_e32 v3, v3, v4, vcc
	v_add_u32_e32 v4, 1, v1
	v_cmp_ge_u32_e32 vcc, v3, v2
	v_add_u32_e32 v3, 1, v5
	s_nop 0
	v_cndmask_b32_e32 v1, v1, v4, vcc
	v_mul_lo_u32 v4, v2, v1
	v_add_u32_e32 v2, v4, v2
	v_cmp_ne_u32_e32 vcc, v3, v2
	s_and_saveexec_b64 s[12:13], vcc
	s_xor_b64 s[12:13], exec, s[12:13]
	s_cbranch_execz .LBB0_644
	s_waitcnt lgkmcnt(0)
	v_mov_b32_e32 v0, 0x2000
	global_load_dword v0, v0, s[10:11] offset:1024 sc1
	buffer_inv sc1
	s_add_u32 s18, s10, 0x2400
	s_addc_u32 s19, s11, 0
	s_waitcnt vmcnt(0)
	v_cmp_eq_u32_e32 vcc, v0, v1
	s_and_saveexec_b64 s[14:15], vcc
	s_cbranch_execz .LBB0_643
	s_add_u32 s16, s8, 0x4200
	s_addc_u32 s17, s9, 0
	s_mov_b32 s30, 1
	s_mov_b64 s[20:21], 0
	v_mov_b32_e32 v0, 0
	s_branch .LBB0_634

.LBB0_643:
	s_or_b64 exec, exec, s[14:15]
	s_waitcnt vmcnt(0)
	s_waitcnt vmcnt(0)

.LBB0_1130:
	s_or_b64 exec, exec, s[16:17]
	v_cvt_f32_u32_e32 v4, v2
	s_waitcnt vmcnt(0)
	v_readfirstlane_b32 s12, v3
	v_sub_u32_e32 v3, 0, v2
	v_rcp_iflag_f32_e32 v4, v4
	v_add_u32_e32 v5, s12, v1
	v_mul_f32_e32 v4, 0x4f7ffffe, v4
	v_cvt_u32_f32_e32 v4, v4
	v_mul_lo_u32 v1, v3, v4
	v_mul_hi_u32 v1, v4, v1
	v_add_u32_e32 v1, v4, v1
	v_mul_hi_u32 v1, v5, v1
	v_mul_lo_u32 v3, v1, v2
	v_sub_u32_e32 v3, v5, v3
	v_add_u32_e32 v4, 1, v1
	v_cmp_ge_u32_e32 vcc, v3, v2
	s_nop 1
	v_cndmask_b32_e32 v1, v1, v4, vcc
	v_sub_u32_e32 v4, v3, v2
	v_cndmask_b32_e32 v3, v3, v4, vcc
	v_add_u32_e32 v4, 1, v1
	v_cmp_ge_u32_e32 vcc, v3, v2
	v_add_u32_e32 v3, 1, v5
	s_nop 0
	v_cndmask_b32_e32 v1, v1, v4, vcc
	v_mul_lo_u32 v4, v2, v1
	v_add_u32_e32 v2, v4, v2
	v_cmp_ne_u32_e32 vcc, v3, v2
	s_and_saveexec_b64 s[12:13], vcc
	s_xor_b64 s[12:13], exec, s[12:13]
	s_cbranch_execz .LBB0_1144
	s_waitcnt lgkmcnt(0)
	v_mov_b32_e32 v0, 0x2000
	global_load_dword v0, v0, s[10:11] offset:1024 sc1
	buffer_inv sc1
	s_add_u32 s20, s10, 0x2400
	s_addc_u32 s21, s11, 0
	s_waitcnt vmcnt(0)
	v_cmp_eq_u32_e32 vcc, v0, v1
	s_and_saveexec_b64 s[16:17], vcc
	s_cbranch_execz .LBB0_1143
	s_add_u32 s18, s8, 0x4200
	s_addc_u32 s19, s9, 0
	s_mov_b32 s33, 1
	s_mov_b64 s[22:23], 0
	v_mov_b32_e32 v0, 0
	s_branch .LBB0_1134

.LBB0_1143:
	s_or_b64 exec, exec, s[16:17]
	s_waitcnt vmcnt(0)
	s_waitcnt vmcnt(0)
